# postA token-local row loop: XCD-aware blocks of 68 consecutive rows per workgroup (conv neighbours and P panels stay local)
# speedup vs baseline: 1.0151x; 1.0044x over previous
.LBB0_364:
	s_andn2_b64 vcc, exec, s[4:5]
	s_cbranch_vccnz .LBB0_442
	v_readlane_b32 s6, v253, 2
	s_mov_b64 s[20:21], s[96:97]
	v_mov_b32_e32 v145, v0
	v_readlane_b32 s7, v253, 3
	s_load_dword s74, s[6:7], 0x0
	s_load_dwordx2 s[54:55], s[20:21], 0xb8
	v_readfirstlane_b32 s4, v145
	s_ashr_i32 s4, s4, 6
	v_readlane_b32 s5, v254, 16
	s_add_i32 s4, s4, s5
	v_and_b32_e32 v146, 15, v145
	v_lshlrev_b32_e32 v144, 3, v146
	s_cmpk_gt_i32 s4, 0x43ff
	s_cbranch_scc1 .LBB0_382
	s_load_dwordx8 s[40:47], s[20:21], 0x48
	s_lshl_b32 s52, s80, 7
	s_lshl_b64 s[6:7], s[52:53], 2
	s_mul_i32 s5, s80, 0x1800
	v_and_b32_e32 v58, 63, v145
	s_waitcnt lgkmcnt(0)
	s_mov_b32 s101, s74
	s_mov_b32 s100, 0x4400
	s_cmp_lg_u32 s74, 0x100
	s_cbranch_scc1 .LpA_nomap
	s_lshr_b32 s100, s4, 3
	s_and_b32 s74, s100, 7
	s_lshl_b32 s74, s74, 5
	s_lshr_b32 s100, s100, 3
	s_or_b32 s100, s100, s74
	s_mul_i32 s100, s100, 0x44
	s_and_b32 s74, s4, 7
	s_add_i32 s4, s100, s74
	s_add_i32 s100, s100, 0x44
	s_mov_b32 s74, 1
.LpA_nomap:
	s_add_u32 s8, s40, s6
	s_addc_u32 s9, s41, s7
	s_add_u32 s10, s44, s5
	s_addc_u32 s11, s45, 0
	v_lshlrev_b32_e32 v38, 5, v58
	v_mov_b32_e32 v39, v99
	v_lshl_add_u64 v[10:11], s[10:11], 0, v[38:39]
	s_mov_b64 s[12:13], 0x1000
	v_add_co_u32_e32 v14, vcc, s93, v10
	v_lshl_add_u64 v[12:13], v[10:11], 0, s[12:13]
	s_nop 0
	v_addc_co_u32_e32 v15, vcc, 0, v11, vcc
	global_load_dwordx4 v[2:5], v38, s[10:11] offset:2048
	global_load_dwordx4 v[6:9], v38, s[10:11] offset:2064
	s_nop 0
	global_load_dwordx4 v[10:13], v[12:13], off offset:16
	s_nop 0
	global_load_dwordx4 v[14:17], v[14:15], off
	s_load_dwordx2 s[20:21], s[20:21], 0x68
	s_lshl_b32 s52, s80, 9
	s_lshl_b64 s[36:37], s[52:53], 2
	s_add_u32 s40, s46, s36
	s_addc_u32 s41, s47, s37
	s_waitcnt lgkmcnt(0)
	s_add_u32 s20, s20, s36
	v_lshlrev_b32_e32 v54, 2, v144
	s_addc_u32 s21, s21, s37
	global_load_dwordx4 v[18:21], v38, s[10:11]
	global_load_dwordx4 v[22:25], v38, s[10:11] offset:16
	global_load_dwordx4 v[26:29], v38, s[40:41]
	global_load_dwordx4 v[30:33], v38, s[40:41] offset:16
	global_load_dwordx4 v[34:37], v38, s[20:21]
	s_nop 0
	global_load_dwordx4 v[38:41], v38, s[20:21] offset:16
	s_nop 0
	global_load_dwordx4 v[42:45], v54, s[8:9] offset:16
	global_load_dwordx4 v[46:49], v54, s[8:9]
	s_lshl_b32 s36, s74, 3
	s_add_u32 s56, s54, 0x195d0000
	s_addc_u32 s57, s55, 0
	s_add_u32 s6, s42, s6
	s_addc_u32 s7, s43, s7
	global_load_dwordx4 v[50:53], v54, s[6:7] offset:16
	s_nop 0
	global_load_dwordx4 v[54:57], v54, s[6:7]
	v_lshlrev_b32_e32 v98, 4, v58
	v_lshl_add_u64 v[116:117], s[54:55], 0, v[98:99]
	s_mov_b64 s[6:7], 0x33f24000
	s_ashr_i32 s5, s4, 31
	v_lshl_add_u64 v[118:119], v[116:117], 0, s[6:7]
	s_lshl_b64 s[6:7], s[4:5], 10
	s_add_u32 s58, s54, s6
	v_and_b32_e32 v59, 4, v145
	v_lshlrev_b32_e32 v60, 2, v145
	v_and_b32_e32 v62, 64, v1
	s_addc_u32 s59, s55, s7
	s_ashr_i32 s37, s36, 31
	v_xor_b32_e32 v61, 1, v1
	v_cmp_eq_u32_e64 s[42:43], 0, v59
	v_and_b32_e32 v59, 12, v60
	v_add_u32_e32 v60, 64, v62
	s_lshl_b64 s[60:61], s[36:37], 10
	s_mul_i32 s7, s4, 0x1400
	v_xor_b32_e32 v63, 2, v1
	v_cmp_lt_i32_e32 vcc, v61, v60
	s_mul_hi_i32 s6, s4, 0x1400
	s_add_u32 s7, s54, s7
	v_xor_b32_e32 v64, 4, v1
	v_cmp_lt_u32_e64 s[44:45], 31, v58
	v_cndmask_b32_e32 v58, v1, v61, vcc
	v_cmp_lt_i32_e32 vcc, v63, v60
	s_addc_u32 s6, s55, s6
	v_xor_b32_e32 v65, 8, v1
	v_cndmask_b32_e32 v61, v1, v63, vcc
	v_cmp_lt_i32_e32 vcc, v64, v60
	s_add_u32 s62, s7, 0x2c824c00
	v_xor_b32_e32 v66, 16, v1
	v_cndmask_b32_e32 v62, v1, v64, vcc
	v_cmp_lt_i32_e32 vcc, v65, v60
	s_addc_u32 s63, s6, 0
	s_lshl_b64 s[6:7], s[4:5], 11
	v_xor_b32_e32 v67, 32, v1
	v_cndmask_b32_e32 v63, v1, v65, vcc
	v_cmp_lt_i32_e32 vcc, v66, v60
	s_add_u32 s64, s54, s6
	s_addc_u32 s65, s55, s7
	v_cndmask_b32_e32 v64, v1, v66, vcc
	v_cmp_lt_i32_e32 vcc, v67, v60
	s_lshl_b64 s[66:67], s[36:37], 11
	s_mul_i32 s6, s4, 0x2800
	v_cndmask_b32_e32 v60, v1, v67, vcc
	s_mul_hi_i32 s5, s4, 0x2800
	s_add_u32 s68, s54, s6
	v_cmp_gt_u32_e64 s[40:41], 8, v146
	v_lshlrev_b32_e32 v147, 2, v58
	v_lshlrev_b32_e32 v148, 2, v61
	v_lshlrev_b32_e32 v149, 2, v62
	v_lshlrev_b32_e32 v150, 2, v63
	v_lshlrev_b32_e32 v151, 2, v64
	v_lshlrev_b32_e32 v152, 2, v60
	s_addc_u32 s69, s55, s5
	v_lshlrev_b32_e32 v153, 4, v59
	s_waitcnt vmcnt(0)
	v_mov_b32_e32 v124, v5
	v_mov_b32_e32 v120, v9
	v_mov_b32_e32 v122, v7
	v_mov_b32_e32 v126, v3
	v_mov_b32_e32 v128, v13
	v_mov_b32_e32 v130, v11
	v_mov_b32_e32 v132, v17
	v_mov_b32_e32 v134, v15
	s_branch .LBB0_369

.LBB0_368:
	s_add_i32 s4, s4, s36
	s_add_u32 s58, s58, s60
	s_addc_u32 s59, s59, s61
	s_mul_i32 s5, s74, 0xa000
	s_add_u32 s62, s62, s5
	s_mul_hi_i32 s5, s36, 0x1400
	s_addc_u32 s63, s63, s5
	s_add_u32 s64, s64, s66
	s_addc_u32 s65, s65, s67
	s_mul_i32 s5, s74, 0x14000
	s_add_u32 s68, s68, s5
	s_mul_hi_i32 s5, s36, 0x2800
	s_addc_u32 s69, s69, s5
	s_cmp_ge_i32 s4, s100
	s_cbranch_scc1 .LpA_end

.LpA_end:
	s_mov_b32 s74, s101
